# P0: the 1152 second w_in transpose items dealt out 9 per 16 consecutive waves (5/4 extra per workgroup) instead of all to workgroups 0..143
# baseline (speedup 1.0000x reference)
; #define LAS __attribute__((address_space(3)))
; template <bool PERMUTE>
; __device__ __forceinline__ void p0_transpose_item(const float* W, int K, int N, bf16* WT, LAS float* scr, int item, int lane) {
;     const int nblk = N / 32, kb = item / nblk, nb = item % nblk, k0 = 64 * kb, n0 = 32 * nb;
;     float wv[32];
; #pragma unroll
;     for (int i = 0; i < 32; ++i) wv[i] = __builtin_nontemporal_load(W + (size_t)(k0 + 2 * i + (lane >> 5)) * N + n0 + (lane & 31));
; #pragma unroll
;     for (int i = 0; i < 32; ++i) scr[(2 * i + (lane >> 5)) * 33 + (lane & 31)] = wv[i];
; __global__ void __launch_bounds__(NWAVES * 64, 2) fwd_megakernel(Args a) {
;     ...
;             { const int kb = gw >> 7, nb = gw & 127; p0_transpose_item<true>(a.w_in, DM, NPROJ, WIN, scr, kb * (NPROJ / 32) + nb, lane); }
.LBB0_32:
	s_andn2_b64 vcc, exec, s[2:3]
	s_cbranch_vccnz .LBB0_67
	v_readlane_b32 s2, v253, 25
	v_readlane_b32 s3, v253, 26
	s_mov_b32 s4, s2
	s_ashr_i32 s2, s2, 7
	s_and_b32 s3, s4, 0x7f
	s_mulk_i32 s2, 0xc8
	s_add_i32 s2, s2, s3
	s_mul_hi_i32 s3, s2, 0x51eb851f
	s_lshr_b32 s4, s3, 31
	s_ashr_i32 s3, s3, 6
	s_add_i32 s3, s3, s4
	s_mul_i32 s4, s3, 0xc8
	s_sub_i32 s8, s2, s4
	s_lshl_b32 s2, s8, 5
	s_lshl_b32 s4, s3, 6
	s_ashr_i32 s3, s2, 31
	v_readlane_b32 s12, v253, 4
	s_lshl_b64 s[6:7], s[2:3], 2
	v_readlane_b32 s16, v253, 8
	v_lshrrev_b32_e32 v14, 5, v231
	v_readlane_b32 s17, v253, 9
	s_add_u32 s6, s16, s6
	v_and_b32_e32 v0, 31, v230
	v_or_b32_e32 v15, s4, v14
	s_addc_u32 s7, s17, s7
	v_mov_b32_e32 v5, 0
	v_lshlrev_b32_e32 v4, 2, v0
	v_lshl_add_u64 v[0:1], s[6:7], 0, v[4:5]
	s_movk_i32 s3, 0x6400
	v_or_b32_e32 v5, 2, v15
	v_mad_i64_i32 v[6:7], s[6:7], v5, s3, v[0:1]
	v_or_b32_e32 v5, 4, v15
	v_mad_i64_i32 v[8:9], s[6:7], v5, s3, v[0:1]
	v_or_b32_e32 v5, 6, v15
	v_mad_i64_i32 v[10:11], s[6:7], v5, s3, v[0:1]
	v_or_b32_e32 v5, 8, v15
	v_mad_i64_i32 v[12:13], s[6:7], v5, s3, v[0:1]
	v_or_b32_e32 v5, 10, v15
	v_mad_i64_i32 v[16:17], s[6:7], v5, s3, v[0:1]
	v_or_b32_e32 v5, 12, v15
	v_mad_i64_i32 v[2:3], s[6:7], v15, s3, v[0:1]
	v_mad_i64_i32 v[18:19], s[6:7], v5, s3, v[0:1]
	v_or_b32_e32 v5, 14, v15
	v_mad_i64_i32 v[20:21], s[6:7], v5, s3, v[0:1]
	global_load_dword v5, v[2:3], off nt
	global_load_dword v22, v[6:7], off nt
	global_load_dword v23, v[8:9], off nt
	global_load_dword v24, v[10:11], off nt
	global_load_dword v25, v[12:13], off nt
	global_load_dword v26, v[16:17], off nt
	global_load_dword v27, v[18:19], off nt
	global_load_dword v28, v[20:21], off nt
	v_or_b32_e32 v2, 16, v15
	v_mad_i64_i32 v[2:3], s[6:7], v2, s3, v[0:1]
	v_or_b32_e32 v6, 18, v15
	v_or_b32_e32 v8, 20, v15
	v_or_b32_e32 v10, 22, v15
	v_or_b32_e32 v12, 24, v15
	v_or_b32_e32 v16, 26, v15
	v_or_b32_e32 v18, 28, v15
	v_or_b32_e32 v20, 30, v15
	v_mad_i64_i32 v[6:7], s[6:7], v6, s3, v[0:1]
	v_mad_i64_i32 v[8:9], s[6:7], v8, s3, v[0:1]
	v_mad_i64_i32 v[10:11], s[6:7], v10, s3, v[0:1]
	v_mad_i64_i32 v[12:13], s[6:7], v12, s3, v[0:1]
	v_mad_i64_i32 v[16:17], s[6:7], v16, s3, v[0:1]
	v_mad_i64_i32 v[18:19], s[6:7], v18, s3, v[0:1]
	v_mad_i64_i32 v[20:21], s[6:7], v20, s3, v[0:1]
	global_load_dword v29, v[2:3], off nt
	global_load_dword v30, v[6:7], off nt
	global_load_dword v31, v[8:9], off nt
	global_load_dword v32, v[10:11], off nt
	global_load_dword v33, v[12:13], off nt
	global_load_dword v34, v[16:17], off nt
	global_load_dword v35, v[18:19], off nt
	global_load_dword v36, v[20:21], off nt
	v_or_b32_e32 v2, 32, v15
	v_mad_i64_i32 v[2:3], s[6:7], v2, s3, v[0:1]
	v_or_b32_e32 v6, 34, v15
	v_or_b32_e32 v8, 36, v15
	v_or_b32_e32 v10, 38, v15
	v_or_b32_e32 v12, 40, v15
	v_or_b32_e32 v16, 42, v15
	v_or_b32_e32 v18, 44, v15
	v_or_b32_e32 v20, 46, v15
	v_mad_i64_i32 v[6:7], s[6:7], v6, s3, v[0:1]
	v_mad_i64_i32 v[8:9], s[6:7], v8, s3, v[0:1]
	v_mad_i64_i32 v[10:11], s[6:7], v10, s3, v[0:1]
	v_mad_i64_i32 v[12:13], s[6:7], v12, s3, v[0:1]
	v_mad_i64_i32 v[16:17], s[6:7], v16, s3, v[0:1]
	v_mad_i64_i32 v[18:19], s[6:7], v18, s3, v[0:1]
	v_mad_i64_i32 v[20:21], s[6:7], v20, s3, v[0:1]
	global_load_dword v37, v[2:3], off nt
	global_load_dword v38, v[6:7], off nt
	global_load_dword v39, v[8:9], off nt
	global_load_dword v40, v[10:11], off nt
	global_load_dword v41, v[12:13], off nt
	global_load_dword v42, v[16:17], off nt
	global_load_dword v43, v[18:19], off nt
	global_load_dword v44, v[20:21], off nt
	v_or_b32_e32 v2, 48, v15
	v_mad_i64_i32 v[2:3], s[6:7], v2, s3, v[0:1]
	v_or_b32_e32 v6, 50, v15
	v_or_b32_e32 v8, 52, v15
	v_or_b32_e32 v10, 54, v15
	v_or_b32_e32 v12, 56, v15
	v_or_b32_e32 v16, 58, v15
	v_or_b32_e32 v18, 60, v15
	v_or_b32_e32 v15, 62, v15
	v_mad_i64_i32 v[6:7], s[6:7], v6, s3, v[0:1]
	v_mad_i64_i32 v[8:9], s[6:7], v8, s3, v[0:1]
	v_mad_i64_i32 v[10:11], s[6:7], v10, s3, v[0:1]
	v_mad_i64_i32 v[12:13], s[6:7], v12, s3, v[0:1]
	v_mad_i64_i32 v[16:17], s[6:7], v16, s3, v[0:1]
	v_mad_i64_i32 v[18:19], s[6:7], v18, s3, v[0:1]
	v_mad_i64_i32 v[0:1], s[6:7], v15, s3, v[0:1]
	global_load_dword v15, v[2:3], off nt
	global_load_dword v20, v[6:7], off nt
	global_load_dword v21, v[8:9], off nt
	global_load_dword v45, v[10:11], off nt
	global_load_dword v46, v[12:13], off nt
	global_load_dword v47, v[16:17], off nt
	global_load_dword v48, v[18:19], off nt
	global_load_dword v49, v[0:1], off nt
	v_readlane_b32 s5, v253, 30
	s_movk_i32 s3, 0x84
	v_lshrrev_b32_e32 v12, 3, v231
	v_add_u32_e32 v18, s5, v4
	v_mad_u32_u24 v0, v14, s3, v18
	v_add_u32_e32 v1, 0x400, v0
	s_waitcnt vmcnt(30)
	ds_write2_b32 v0, v5, v22 offset1:66
	s_waitcnt vmcnt(28)
	ds_write2_b32 v0, v23, v24 offset0:132 offset1:198
	s_waitcnt vmcnt(26)
	ds_write2_b32 v1, v25, v26 offset0:8 offset1:74
	s_waitcnt vmcnt(24)
	ds_write2_b32 v1, v27, v28 offset0:140 offset1:206
	v_add_u32_e32 v1, 0x800, v0
	s_waitcnt vmcnt(22)
	ds_write2_b32 v1, v29, v30 offset0:16 offset1:82
	s_waitcnt vmcnt(20)
	ds_write2_b32 v1, v31, v32 offset0:148 offset1:214
	v_add_u32_e32 v1, 0xc00, v0
	s_waitcnt vmcnt(18)
	ds_write2_b32 v1, v33, v34 offset0:24 offset1:90
	s_waitcnt vmcnt(16)
	ds_write2_b32 v1, v35, v36 offset0:156 offset1:222
	v_add_u32_e32 v1, 0x1000, v0
	s_waitcnt vmcnt(14)
	ds_write2_b32 v1, v37, v38 offset0:32 offset1:98
	s_waitcnt vmcnt(12)
	ds_write2_b32 v1, v39, v40 offset0:164 offset1:230
	v_add_u32_e32 v1, 0x1400, v0
	s_waitcnt vmcnt(10)
	ds_write2_b32 v1, v41, v42 offset0:40 offset1:106
	s_waitcnt vmcnt(8)
	ds_write2_b32 v1, v43, v44 offset0:172 offset1:238
	v_add_u32_e32 v1, 0x1800, v0
	v_add_u32_e32 v0, 0x1c00, v0
	s_waitcnt vmcnt(6)
; #define LAS __attribute__((address_space(3)))
; #define LDS_WAIT() asm volatile("s_waitcnt lgkmcnt(0)" ::: "memory")
; __device__ __forceinline__ unsigned pk2(float lo, float hi) { return pg8::cvt_pk_bf16(lo, hi); }
; template <bool PERMUTE>
; __device__ __forceinline__ void p0_transpose_item(const float* W, int K, int N, bf16* WT, LAS float* scr, int item, int lane) {
;     ...
;     const int c = lane & 7;
; #pragma unroll
;     for (int j = 0; j < 4; ++j) { const int n = (lane >> 3) + 8 * j; const LAS float* s = scr + (8 * c) * 33 + n;
;         v4u o; o.x = pk2(s[0 * 33], s[1 * 33]); o.y = pk2(s[2 * 33], s[3 * 33]); o.z = pk2(s[4 * 33], s[5 * 33]); o.w = pk2(s[6 * 33], s[7 * 33]);
;         const int dr = PERMUTE ? win_dst_row(n0 + n) : (n0 + n);
;         if (PERMUTE && n0 < 4096) __builtin_nontemporal_store(o, (v4u*)(WT + (size_t)dr * K + k0 + 8 * c));
;         else *(v4u*)(WT + (size_t)dr * K + k0 + 8 * c) = o; }
;     LDS_WAIT(); asm volatile("" ::: "memory");
; }
; __global__ void __launch_bounds__(NWAVES * 64, 2) fwd_megakernel(Args a) {
;     ...
;             if (gw < 1152) { const int kb = gw / 72, nb = 128 + gw % 72; p0_transpose_item<true>(a.w_in, DM, NPROJ, WIN, scr, kb * (NPROJ / 32) + nb, lane); }
	ds_write2_b32 v1, v15, v20 offset0:48 offset1:114
	s_waitcnt vmcnt(4)
	ds_write2_b32 v1, v21, v45 offset0:180 offset1:246
	s_waitcnt vmcnt(2)
	ds_write2_b32 v0, v46, v47 offset0:56 offset1:122
	s_waitcnt vmcnt(0)
	ds_write2_b32 v0, v48, v49 offset0:188 offset1:254
	v_lshlrev_b32_e32 v0, 3, v230
	v_and_b32_e32 v5, 56, v0
	s_waitcnt lgkmcnt(0)
	v_mul_u32_u24_e32 v0, 0x84, v5
	v_lshlrev_b32_e32 v1, 2, v12
	v_add3_u32 v13, s5, v0, v1
	ds_read2_b32 v[0:1], v13 offset1:33
	s_waitcnt lgkmcnt(0)
	v_cvt_pk_bf16_f32 v0, v0, v1
	ds_read2_b32 v[2:3], v13 offset0:66 offset1:99
	s_lshl_b32 s3, s8, 7
	s_lshl_b32 s5, s8, 1
	s_waitcnt lgkmcnt(0)
	v_cvt_pk_bf16_f32 v1, v2, v3
	ds_read2_b32 v[2:3], v13 offset0:132 offset1:165
	s_and_b32 s3, s3, 0xf00
	s_and_b32 s5, s5, 0xffffff80
	s_lshr_b32 s6, s8, 1
	s_waitcnt lgkmcnt(0)
	v_cvt_pk_bf16_f32 v2, v2, v3
	ds_read2_b32 v[6:7], v13 offset0:198 offset1:231
	s_and_b32 s6, s6, 16
	s_add_i32 s3, s3, s5
	s_and_b32 s9, s2, 0x7fffffe0
	s_or_b32 s10, s3, s6
	s_waitcnt lgkmcnt(0)
	v_cvt_pk_bf16_f32 v3, v6, v7
	v_or_b32_e32 v6, s2, v12
	s_movk_i32 s3, 0xfff
	v_bfe_u32 v15, v231, 3, 2
	s_addk_i32 s9, 0xf000
	v_cmp_lt_i32_e32 vcc, s3, v6
	v_readlane_b32 s13, v253, 5
	v_readlane_b32 s14, v253, 6
	v_readlane_b32 s15, v253, 7
	v_readlane_b32 s18, v253, 10
	v_readlane_b32 s19, v253, 11
	v_readlane_b32 s20, v253, 12
	v_readlane_b32 s21, v253, 13
	v_readlane_b32 s22, v253, 14
	v_readlane_b32 s23, v253, 15
	v_readlane_b32 s24, v253, 16
	v_readlane_b32 s25, v253, 17
	v_readlane_b32 s26, v253, 18
	v_readlane_b32 s27, v253, 19
	s_and_saveexec_b64 s[6:7], vcc
	s_xor_b64 s[6:7], exec, s[6:7]
	v_lshlrev_b32_e32 v6, 2, v6
	v_and_b32_e32 v6, 16, v6
	v_or3_b32 v10, v15, v6, s9
	s_or_saveexec_b64 s[6:7], s[6:7]
	s_addk_i32 s10, 0x900
	s_xor_b64 exec, exec, s[6:7]
	s_lshl_b32 s3, s8, 6
	v_and_or_b32 v6, s3, 64, v12
	v_or_b32_e32 v10, s10, v6
	s_or_b64 exec, exec, s[6:7]
	s_ashr_i32 s5, s4, 31
	s_lshl_b64 s[4:5], s[4:5], 1
	s_add_u32 s4, s52, s4
	s_addc_u32 s5, s53, s5
	v_mov_b32_e32 v7, 0
	v_lshlrev_b32_e32 v6, 1, v5
	v_ashrrev_i32_e32 v11, 31, v10
	v_lshl_add_u64 v[8:9], s[4:5], 0, v[6:7]
	v_lshlrev_b64 v[10:11], 11, v[10:11]
	ds_read2_b32 v[16:17], v13 offset0:8 offset1:41
	v_lshl_add_u64 v[10:11], v[8:9], 0, v[10:11]
	global_store_dwordx4 v[10:11], v[0:3], off
	s_movk_i32 s3, 0xfff
	s_waitcnt lgkmcnt(0)
	v_cvt_pk_bf16_f32 v0, v16, v17
	ds_read2_b32 v[2:3], v13 offset0:74 offset1:107
	v_or_b32_e32 v16, 8, v12
	s_waitcnt lgkmcnt(0)
	v_cvt_pk_bf16_f32 v1, v2, v3
	ds_read2_b32 v[2:3], v13 offset0:140 offset1:173
	v_or_b32_e32 v5, s2, v16
	s_waitcnt lgkmcnt(0)
	v_cvt_pk_bf16_f32 v2, v2, v3
	ds_read2_b32 v[10:11], v13 offset0:206 offset1:239
	v_cmp_lt_i32_e32 vcc, s3, v5
	s_waitcnt lgkmcnt(0)
	v_cvt_pk_bf16_f32 v3, v10, v11
	s_and_saveexec_b64 s[4:5], vcc
	s_xor_b64 s[4:5], exec, s[4:5]
	v_lshlrev_b32_e32 v5, 2, v5
	v_and_or_b32 v5, v5, 16, s9
	v_or3_b32 v10, v5, v12, 4
	s_andn2_saveexec_b64 s[4:5], s[4:5]
	s_lshl_b32 s3, s8, 6
	v_and_or_b32 v5, s3, 64, v16
	v_or_b32_e32 v10, s10, v5
	s_or_b64 exec, exec, s[4:5]
	v_ashrrev_i32_e32 v11, 31, v10
	v_lshlrev_b64 v[10:11], 11, v[10:11]
	v_lshl_add_u64 v[10:11], v[8:9], 0, v[10:11]
	ds_read2_b32 v[20:21], v13 offset0:16 offset1:49
	global_store_dwordx4 v[10:11], v[0:3], off
	v_or_b32_e32 v19, 16, v12
	s_movk_i32 s3, 0xfff
	s_waitcnt lgkmcnt(0)
	v_cvt_pk_bf16_f32 v0, v20, v21
	ds_read2_b32 v[2:3], v13 offset0:82 offset1:115
	s_waitcnt lgkmcnt(0)
	v_cvt_pk_bf16_f32 v1, v2, v3
	ds_read2_b32 v[2:3], v13 offset0:148 offset1:181
	v_or_b32_e32 v5, s2, v19
	s_waitcnt lgkmcnt(0)
	v_cvt_pk_bf16_f32 v2, v2, v3
	ds_read2_b32 v[10:11], v13 offset0:214 offset1:247
	v_cmp_lt_i32_e32 vcc, s3, v5
	s_waitcnt lgkmcnt(0)
	v_cvt_pk_bf16_f32 v3, v10, v11
	s_and_saveexec_b64 s[4:5], vcc
	s_xor_b64 s[4:5], exec, s[4:5]
	v_lshlrev_b32_e32 v5, 2, v5
	v_and_or_b32 v5, v5, 16, s9
	v_or3_b32 v10, v5, v15, 8
	s_andn2_saveexec_b64 s[4:5], s[4:5]
	v_lshlrev_b32_e32 v5, 1, v5
	v_and_b32_e32 v5, 0x60, v5
	v_or3_b32 v10, v5, v12, s10
	s_or_b64 exec, exec, s[4:5]
	v_ashrrev_i32_e32 v11, 31, v10
	v_lshlrev_b64 v[10:11], 11, v[10:11]
	v_lshl_add_u64 v[10:11], v[8:9], 0, v[10:11]
	ds_read2_b32 v[20:21], v13 offset0:24 offset1:57
	global_store_dwordx4 v[10:11], v[0:3], off
	v_or_b32_e32 v17, 24, v12
	v_or_b32_e32 v5, s2, v17
	s_waitcnt lgkmcnt(0)
	v_cvt_pk_bf16_f32 v0, v20, v21
	ds_read2_b32 v[2:3], v13 offset0:90 offset1:123
	s_waitcnt lgkmcnt(0)
	v_cvt_pk_bf16_f32 v1, v2, v3
	ds_read2_b32 v[2:3], v13 offset0:156 offset1:189
	s_waitcnt lgkmcnt(0)
	v_cvt_pk_bf16_f32 v2, v2, v3
	ds_read2_b32 v[10:11], v13 offset0:222 offset1:255
	v_cmp_lt_i32_e32 vcc, s3, v5
	s_waitcnt lgkmcnt(0)
	v_cvt_pk_bf16_f32 v3, v10, v11
	s_and_saveexec_b64 s[2:3], vcc
	s_xor_b64 s[2:3], exec, s[2:3]
	v_lshlrev_b32_e32 v5, 2, v5
	v_and_or_b32 v5, v5, 16, s9
	v_or3_b32 v10, v5, v12, 12
	s_andn2_saveexec_b64 s[2:3], s[2:3]
	v_lshlrev_b32_e32 v5, 1, v5
	v_and_b32_e32 v5, 0x60, v5
	v_and_b32_e32 v7, 15, v17
	v_or3_b32 v10, v5, v7, s10
	s_or_b64 exec, exec, s[2:3]
	v_ashrrev_i32_e32 v11, 31, v10
	v_lshlrev_b64 v[10:11], 11, v[10:11]
	v_lshl_add_u64 v[8:9], v[8:9], 0, v[10:11]
	global_store_dwordx4 v[8:9], v[0:3], off
	s_waitcnt lgkmcnt(0)
	v_readlane_b32 s2, v253, 25
	s_and_b32 s3, s2, 15
	s_and_b32 s4, s3, 1
	s_lshr_b32 s5, s3, 1
	s_cmp_eq_u32 s3, 1
	s_cselect_b32 s5, 8, s5
	s_cselect_b32 s4, 0, s4
	s_cmp_lg_u32 s4, 0
	s_cbranch_scc1 .LBB0_67
; #define LAS __attribute__((address_space(3)))
; template <bool PERMUTE>
; __device__ __forceinline__ void p0_transpose_item(const float* W, int K, int N, bf16* WT, LAS float* scr, int item, int lane) {
;     const int nblk = N / 32, kb = item / nblk, nb = item % nblk, k0 = 64 * kb, n0 = 32 * nb;
;     float wv[32];
; #pragma unroll
;     for (int i = 0; i < 32; ++i) wv[i] = __builtin_nontemporal_load(W + (size_t)(k0 + 2 * i + (lane >> 5)) * N + n0 + (lane & 31));
; #pragma unroll
;     for (int i = 0; i < 32; ++i) scr[(2 * i + (lane >> 5)) * 33 + (lane & 31)] = wv[i];
; __global__ void __launch_bounds__(NWAVES * 64, 2) fwd_megakernel(Args a) {
;     ...
;             if (gw < 1152) { const int kb = gw / 72, nb = 128 + gw % 72; p0_transpose_item<true>(a.w_in, DM, NPROJ, WIN, scr, kb * (NPROJ / 32) + nb, lane); }
	s_lshr_b32 s2, s2, 4
	s_mul_i32 s2, s2, 9
	s_add_i32 s2, s2, s5
	v_readlane_b32 s3, v253, 26
	s_mov_b32 s4, s2
	s_mul_hi_i32 s2, s2, 0x38e38e39
	s_lshr_b32 s3, s2, 31
	s_ashr_i32 s2, s2, 4
	s_add_i32 s2, s2, s3
	s_mul_i32 s3, s2, 0x48
	s_sub_i32 s3, s4, s3
	s_mulk_i32 s2, 0xc8
	s_add_i32 s2, s3, s2
	s_addk_i32 s2, 0x80
	s_mul_hi_i32 s3, s2, 0x51eb851f
	s_lshr_b32 s4, s3, 31
	s_ashr_i32 s3, s3, 6
	s_add_i32 s3, s3, s4
	s_mul_i32 s4, s3, 0xc8
	s_sub_i32 s8, s2, s4
	s_lshl_b32 s2, s8, 5
	s_lshl_b32 s4, s3, 6
	s_ashr_i32 s3, s2, 31
	v_readlane_b32 s12, v253, 4
	s_lshl_b64 s[6:7], s[2:3], 2
	v_readlane_b32 s16, v253, 8
	v_readlane_b32 s17, v253, 9
	s_add_u32 s6, s16, s6
	s_addc_u32 s7, s17, s7
	v_mov_b32_e32 v5, 0
	v_or_b32_e32 v7, s4, v14
	v_lshl_add_u64 v[0:1], s[6:7], 0, v[4:5]
	s_movk_i32 s3, 0x6400
	v_mad_i64_i32 v[2:3], s[6:7], v7, s3, v[0:1]
	v_or_b32_e32 v4, 2, v7
	v_or_b32_e32 v8, 4, v7
	v_or_b32_e32 v10, 6, v7
	v_or_b32_e32 v20, 8, v7
	v_or_b32_e32 v22, 10, v7
	v_or_b32_e32 v24, 12, v7
	v_or_b32_e32 v26, 14, v7
	v_mad_i64_i32 v[4:5], s[6:7], v4, s3, v[0:1]
	v_mad_i64_i32 v[8:9], s[6:7], v8, s3, v[0:1]
	v_mad_i64_i32 v[10:11], s[6:7], v10, s3, v[0:1]
	v_mad_i64_i32 v[20:21], s[6:7], v20, s3, v[0:1]
	v_mad_i64_i32 v[22:23], s[6:7], v22, s3, v[0:1]
	v_mad_i64_i32 v[24:25], s[6:7], v24, s3, v[0:1]
	v_mad_i64_i32 v[26:27], s[6:7], v26, s3, v[0:1]
	global_load_dword v28, v[2:3], off nt
	global_load_dword v29, v[4:5], off nt
	global_load_dword v30, v[8:9], off nt
	global_load_dword v31, v[10:11], off nt
	global_load_dword v32, v[20:21], off nt
	global_load_dword v33, v[22:23], off nt
	global_load_dword v34, v[24:25], off nt
	global_load_dword v35, v[26:27], off nt
	v_or_b32_e32 v2, 16, v7
	v_mad_i64_i32 v[2:3], s[6:7], v2, s3, v[0:1]
	v_or_b32_e32 v4, 18, v7
	v_or_b32_e32 v8, 20, v7
	v_or_b32_e32 v10, 22, v7
	v_or_b32_e32 v20, 24, v7
	v_or_b32_e32 v22, 26, v7
	v_or_b32_e32 v24, 28, v7
	v_or_b32_e32 v26, 30, v7
	v_mad_i64_i32 v[4:5], s[6:7], v4, s3, v[0:1]
	v_mad_i64_i32 v[8:9], s[6:7], v8, s3, v[0:1]
	v_mad_i64_i32 v[10:11], s[6:7], v10, s3, v[0:1]
	v_mad_i64_i32 v[20:21], s[6:7], v20, s3, v[0:1]
	v_mad_i64_i32 v[22:23], s[6:7], v22, s3, v[0:1]
	v_mad_i64_i32 v[24:25], s[6:7], v24, s3, v[0:1]
	v_mad_i64_i32 v[26:27], s[6:7], v26, s3, v[0:1]
	global_load_dword v36, v[2:3], off nt
	global_load_dword v37, v[4:5], off nt
	global_load_dword v38, v[8:9], off nt
	global_load_dword v39, v[10:11], off nt
	global_load_dword v40, v[20:21], off nt
	global_load_dword v41, v[22:23], off nt
	global_load_dword v42, v[24:25], off nt
	global_load_dword v43, v[26:27], off nt
	v_or_b32_e32 v2, 32, v7
	v_mad_i64_i32 v[2:3], s[6:7], v2, s3, v[0:1]
	v_or_b32_e32 v4, 34, v7
	v_or_b32_e32 v8, 36, v7
	v_or_b32_e32 v10, 38, v7
	v_or_b32_e32 v20, 40, v7
	v_or_b32_e32 v22, 42, v7
	v_or_b32_e32 v24, 44, v7
	v_or_b32_e32 v26, 46, v7
	v_mad_i64_i32 v[4:5], s[6:7], v4, s3, v[0:1]
	v_mad_i64_i32 v[8:9], s[6:7], v8, s3, v[0:1]
	v_mad_i64_i32 v[10:11], s[6:7], v10, s3, v[0:1]
	v_mad_i64_i32 v[20:21], s[6:7], v20, s3, v[0:1]
	v_mad_i64_i32 v[22:23], s[6:7], v22, s3, v[0:1]
	v_mad_i64_i32 v[24:25], s[6:7], v24, s3, v[0:1]
	v_mad_i64_i32 v[26:27], s[6:7], v26, s3, v[0:1]
	global_load_dword v44, v[2:3], off nt
	global_load_dword v45, v[4:5], off nt
	global_load_dword v46, v[8:9], off nt
	global_load_dword v47, v[10:11], off nt
	global_load_dword v48, v[20:21], off nt
	global_load_dword v49, v[22:23], off nt
	global_load_dword v50, v[24:25], off nt
	global_load_dword v51, v[26:27], off nt
	v_or_b32_e32 v2, 48, v7
	v_mad_i64_i32 v[2:3], s[6:7], v2, s3, v[0:1]
	v_or_b32_e32 v4, 50, v7
	v_or_b32_e32 v8, 52, v7
	v_or_b32_e32 v10, 54, v7
	v_or_b32_e32 v20, 56, v7
	v_or_b32_e32 v22, 58, v7
	v_or_b32_e32 v24, 60, v7
	v_or_b32_e32 v7, 62, v7
	v_mad_i64_i32 v[4:5], s[6:7], v4, s3, v[0:1]
	v_mad_i64_i32 v[8:9], s[6:7], v8, s3, v[0:1]
	v_mad_i64_i32 v[10:11], s[6:7], v10, s3, v[0:1]
	v_mad_i64_i32 v[20:21], s[6:7], v20, s3, v[0:1]
	v_mad_i64_i32 v[22:23], s[6:7], v22, s3, v[0:1]
	v_mad_i64_i32 v[24:25], s[6:7], v24, s3, v[0:1]
	v_mad_i64_i32 v[0:1], s[6:7], v7, s3, v[0:1]
	global_load_dword v7, v[2:3], off nt
	global_load_dword v26, v[4:5], off nt
	global_load_dword v27, v[8:9], off nt
	global_load_dword v52, v[10:11], off nt
	global_load_dword v53, v[20:21], off nt
	global_load_dword v54, v[22:23], off nt
	global_load_dword v55, v[24:25], off nt
	global_load_dword v56, v[0:1], off nt
	v_mul_u32_u24_e32 v0, 0x84, v14
	v_add_u32_e32 v0, v18, v0
	v_add_u32_e32 v1, 0x400, v0
	s_waitcnt vmcnt(30)
	ds_write2_b32 v0, v28, v29 offset1:66
	s_waitcnt vmcnt(28)
	ds_write2_b32 v0, v30, v31 offset0:132 offset1:198
	s_waitcnt vmcnt(26)
	ds_write2_b32 v1, v32, v33 offset0:8 offset1:74
	s_waitcnt vmcnt(24)
	ds_write2_b32 v1, v34, v35 offset0:140 offset1:206
	v_add_u32_e32 v1, 0x800, v0
	s_waitcnt vmcnt(22)
	ds_write2_b32 v1, v36, v37 offset0:16 offset1:82
	s_waitcnt vmcnt(20)
	ds_write2_b32 v1, v38, v39 offset0:148 offset1:214
	v_add_u32_e32 v1, 0xc00, v0
	s_waitcnt vmcnt(18)
	ds_write2_b32 v1, v40, v41 offset0:24 offset1:90
	s_waitcnt vmcnt(16)
	ds_write2_b32 v1, v42, v43 offset0:156 offset1:222
	v_add_u32_e32 v1, 0x1000, v0
	s_waitcnt vmcnt(14)
; #define LAS __attribute__((address_space(3)))
; #define LDS_WAIT() asm volatile("s_waitcnt lgkmcnt(0)" ::: "memory")
; __device__ __forceinline__ unsigned pk2(float lo, float hi) { return pg8::cvt_pk_bf16(lo, hi); }
; template <bool PERMUTE>
; __device__ __forceinline__ void p0_transpose_item(const float* W, int K, int N, bf16* WT, LAS float* scr, int item, int lane) {
;     ...
;     for (int i = 0; i < 32; ++i) scr[(2 * i + (lane >> 5)) * 33 + (lane & 31)] = wv[i];
;     LDS_WAIT(); asm volatile("" ::: "memory");
;     const int c = lane & 7;
; #pragma unroll
;     for (int j = 0; j < 4; ++j) { const int n = (lane >> 3) + 8 * j; const LAS float* s = scr + (8 * c) * 33 + n;
;         v4u o; o.x = pk2(s[0 * 33], s[1 * 33]); o.y = pk2(s[2 * 33], s[3 * 33]); o.z = pk2(s[4 * 33], s[5 * 33]); o.w = pk2(s[6 * 33], s[7 * 33]);
;         const int dr = PERMUTE ? win_dst_row(n0 + n) : (n0 + n);
;         if (PERMUTE && n0 < 4096) __builtin_nontemporal_store(o, (v4u*)(WT + (size_t)dr * K + k0 + 8 * c));
;         else *(v4u*)(WT + (size_t)dr * K + k0 + 8 * c) = o; }
;     LDS_WAIT(); asm volatile("" ::: "memory");
; }
	ds_write2_b32 v1, v44, v45 offset0:32 offset1:98
	s_waitcnt vmcnt(12)
	ds_write2_b32 v1, v46, v47 offset0:164 offset1:230
	v_add_u32_e32 v1, 0x1400, v0
	s_waitcnt vmcnt(10)
	ds_write2_b32 v1, v48, v49 offset0:40 offset1:106
	s_waitcnt vmcnt(8)
	ds_write2_b32 v1, v50, v51 offset0:172 offset1:238
	v_add_u32_e32 v1, 0x1800, v0
	v_add_u32_e32 v0, 0x1c00, v0
	s_waitcnt vmcnt(6)
	ds_write2_b32 v1, v7, v26 offset0:48 offset1:114
	s_waitcnt vmcnt(4)
	ds_write2_b32 v1, v27, v52 offset0:180 offset1:246
	s_waitcnt vmcnt(2)
	ds_write2_b32 v0, v53, v54 offset0:56 offset1:122
	s_waitcnt vmcnt(0)
	ds_write2_b32 v0, v55, v56 offset0:188 offset1:254
	s_waitcnt lgkmcnt(0)
	ds_read2_b32 v[0:1], v13 offset1:33
	s_waitcnt lgkmcnt(0)
	v_cvt_pk_bf16_f32 v0, v0, v1
	ds_read2_b32 v[2:3], v13 offset0:66 offset1:99
	s_lshl_b32 s3, s8, 7
	s_lshl_b32 s5, s8, 1
	s_waitcnt lgkmcnt(0)
	v_cvt_pk_bf16_f32 v1, v2, v3
	ds_read2_b32 v[2:3], v13 offset0:132 offset1:165
	s_and_b32 s3, s3, 0xf00
	s_and_b32 s5, s5, 0xffffff80
	s_lshr_b32 s6, s8, 1
	s_waitcnt lgkmcnt(0)
	v_cvt_pk_bf16_f32 v2, v2, v3
	ds_read2_b32 v[4:5], v13 offset0:198 offset1:231
	s_and_b32 s6, s6, 16
	s_add_i32 s3, s3, s5
	s_and_b32 s9, s2, 0x7fffffe0
	s_or_b32 s10, s3, s6
	s_waitcnt lgkmcnt(0)
	v_cvt_pk_bf16_f32 v3, v4, v5
	v_or_b32_e32 v4, s2, v12
	s_movk_i32 s3, 0xfff
	s_addk_i32 s9, 0xf000
	v_cmp_lt_i32_e32 vcc, s3, v4
	v_readlane_b32 s13, v253, 5
	v_readlane_b32 s14, v253, 6
	v_readlane_b32 s15, v253, 7
	v_readlane_b32 s18, v253, 10
	v_readlane_b32 s19, v253, 11
	v_readlane_b32 s20, v253, 12
	v_readlane_b32 s21, v253, 13
	v_readlane_b32 s22, v253, 14
	v_readlane_b32 s23, v253, 15
	v_readlane_b32 s24, v253, 16
	v_readlane_b32 s25, v253, 17
	v_readlane_b32 s26, v253, 18
	v_readlane_b32 s27, v253, 19
	s_and_saveexec_b64 s[6:7], vcc
	s_xor_b64 s[6:7], exec, s[6:7]
	v_lshlrev_b32_e32 v4, 2, v4
	v_and_b32_e32 v4, 16, v4
	v_or3_b32 v8, v15, v4, s9
	s_or_saveexec_b64 s[6:7], s[6:7]
	s_addk_i32 s10, 0x900
	s_xor_b64 exec, exec, s[6:7]
	s_lshl_b32 s3, s8, 6
	v_and_or_b32 v4, s3, 64, v12
	v_or_b32_e32 v8, s10, v4
	s_or_b64 exec, exec, s[6:7]
	s_ashr_i32 s5, s4, 31
	s_lshl_b64 s[4:5], s[4:5], 1
	s_add_u32 s4, s52, s4
	s_addc_u32 s5, s53, s5
	v_mov_b32_e32 v7, 0
	v_ashrrev_i32_e32 v9, 31, v8
	v_lshl_add_u64 v[4:5], s[4:5], 0, v[6:7]
	v_lshlrev_b64 v[8:9], 11, v[8:9]
	ds_read2_b32 v[6:7], v13 offset0:8 offset1:41
	v_lshl_add_u64 v[8:9], v[4:5], 0, v[8:9]
	global_store_dwordx4 v[8:9], v[0:3], off
	s_movk_i32 s3, 0xfff
	s_waitcnt lgkmcnt(0)
	v_cvt_pk_bf16_f32 v0, v6, v7
	ds_read2_b32 v[2:3], v13 offset0:74 offset1:107
	v_or_b32_e32 v7, s2, v16
	s_waitcnt lgkmcnt(0)
	v_cvt_pk_bf16_f32 v1, v2, v3
	ds_read2_b32 v[2:3], v13 offset0:140 offset1:173
	v_cmp_lt_i32_e32 vcc, s3, v7
	s_waitcnt lgkmcnt(0)
	v_cvt_pk_bf16_f32 v2, v2, v3
	ds_read2_b32 v[8:9], v13 offset0:206 offset1:239
	s_waitcnt lgkmcnt(0)
	v_cvt_pk_bf16_f32 v3, v8, v9
	s_and_saveexec_b64 s[4:5], vcc
	s_xor_b64 s[4:5], exec, s[4:5]
	v_lshlrev_b32_e32 v6, 2, v7
	v_and_or_b32 v6, v6, 16, s9
	v_or3_b32 v6, v6, v12, 4
	s_andn2_saveexec_b64 s[4:5], s[4:5]
	s_lshl_b32 s3, s8, 6
	v_and_or_b32 v6, s3, 64, v16
	v_or_b32_e32 v6, s10, v6
	s_or_b64 exec, exec, s[4:5]
	v_ashrrev_i32_e32 v7, 31, v6
	v_lshlrev_b64 v[6:7], 11, v[6:7]
	v_lshl_add_u64 v[6:7], v[4:5], 0, v[6:7]
	ds_read2_b32 v[8:9], v13 offset0:16 offset1:49
	global_store_dwordx4 v[6:7], v[0:3], off
	v_or_b32_e32 v7, s2, v19
	s_movk_i32 s3, 0xfff
	s_waitcnt lgkmcnt(0)
	v_cvt_pk_bf16_f32 v0, v8, v9
	ds_read2_b32 v[2:3], v13 offset0:82 offset1:115
	s_waitcnt lgkmcnt(0)
	v_cvt_pk_bf16_f32 v1, v2, v3
	ds_read2_b32 v[2:3], v13 offset0:148 offset1:181
	v_cmp_lt_i32_e32 vcc, s3, v7
	s_waitcnt lgkmcnt(0)
	v_cvt_pk_bf16_f32 v2, v2, v3
	ds_read2_b32 v[8:9], v13 offset0:214 offset1:247
	s_waitcnt lgkmcnt(0)
	v_cvt_pk_bf16_f32 v3, v8, v9
	s_and_saveexec_b64 s[4:5], vcc
	s_xor_b64 s[4:5], exec, s[4:5]
	v_lshlrev_b32_e32 v6, 2, v7
	v_and_or_b32 v6, v6, 16, s9
	v_or3_b32 v6, v6, v15, 8
	s_andn2_saveexec_b64 s[4:5], s[4:5]
	v_lshlrev_b32_e32 v6, 1, v7
	v_and_b32_e32 v6, 0x60, v6
	v_or3_b32 v6, v6, v12, s10
	s_or_b64 exec, exec, s[4:5]
	v_ashrrev_i32_e32 v7, 31, v6
	v_lshlrev_b64 v[6:7], 11, v[6:7]
	v_lshl_add_u64 v[6:7], v[4:5], 0, v[6:7]
	ds_read2_b32 v[8:9], v13 offset0:24 offset1:57
	global_store_dwordx4 v[6:7], v[0:3], off
	v_or_b32_e32 v7, s2, v17
	s_movk_i32 s2, 0xfff
	s_waitcnt lgkmcnt(0)
	v_cvt_pk_bf16_f32 v0, v8, v9
	ds_read2_b32 v[2:3], v13 offset0:90 offset1:123
	s_waitcnt lgkmcnt(0)
	v_cvt_pk_bf16_f32 v1, v2, v3
	ds_read2_b32 v[2:3], v13 offset0:156 offset1:189
	v_cmp_lt_i32_e32 vcc, s2, v7
	s_waitcnt lgkmcnt(0)
	v_cvt_pk_bf16_f32 v2, v2, v3
	ds_read2_b32 v[8:9], v13 offset0:222 offset1:255
	s_waitcnt lgkmcnt(0)
	v_cvt_pk_bf16_f32 v3, v8, v9
	s_and_saveexec_b64 s[2:3], vcc
	s_xor_b64 s[2:3], exec, s[2:3]
	v_lshlrev_b32_e32 v6, 2, v7
	v_and_or_b32 v6, v6, 16, s9
	v_or3_b32 v6, v6, v12, 12
	s_andn2_saveexec_b64 s[2:3], s[2:3]
	v_lshlrev_b32_e32 v6, 1, v7
	v_and_b32_e32 v6, 0x60, v6
	v_and_b32_e32 v7, 15, v17
	v_or3_b32 v6, v6, v7, s10
	s_or_b64 exec, exec, s[2:3]
	v_ashrrev_i32_e32 v7, 31, v6
	v_lshlrev_b64 v[6:7], 11, v[6:7]
	v_lshl_add_u64 v[4:5], v[4:5], 0, v[6:7]
	global_store_dwordx4 v[4:5], v[0:3], off
	s_waitcnt lgkmcnt(0)
